# strategy 7 instruction selection: NSA sliding-window boundary tiles use one unsigned range compare per element (alternating vcc / SGPR pair) instead of two signed compares + scalar AND
# speedup vs baseline: 1.0069x; 1.0069x over previous
; #define EXP2F(x) __builtin_amdgcn_exp2f(x)
; template <class MaskF>
; __device__ __forceinline__ void qk64(const bf16x8 (&kq)[8], const bf16x8 (&qf)[2], float scale, MaskF maskf, int lane,
;                                      f32x4 (&st)[4]) {
;   const int q = lane >> 4;
; #pragma unroll
;   for (int kt = 0; kt < 4; ++kt) {
;     f32x4 z = {0.f, 0.f, 0.f, 0.f};
;     z = mfma16(kq[2 * kt], qf[0], z);
;     z = mfma16(kq[2 * kt + 1], qf[1], z);
; #pragma unroll
;     for (int r = 0; r < 4; ++r) st[kt][r] = maskf(kt * 16 + q * 4 + r) ? z[r] * scale : -INFINITY;
;   }
; }
; __device__ __forceinline__ void softmax_update(f32x4 (&st)[4], float& m, float& lsum, f32x4 (&o)[4]) {
;   float mx = -1e30f;
; #pragma unroll
;   for (int kt = 0; kt < 4; ++kt)
; #pragma unroll
;     for (int r = 0; r < 4; ++r) mx = fmaxf(mx, st[kt][r]);
;   mx = fmaxf(mx, __shfl_xor(mx, 16));
;   mx = fmaxf(mx, __shfl_xor(mx, 32));
;   const float mnew = fmaxf(m, mx);
;   const float alpha = EXP2F(m - mnew);
;   float ps = 0.f;
; #pragma unroll
;   for (int kt = 0; kt < 4; ++kt)
; #pragma unroll
;     for (int r = 0; r < 4; ++r) {
;       const float pv = EXP2F(st[kt][r] - mnew);
;       st[kt][r] = pv;
;       ps += pv;
;     }
;   lsum = lsum * alpha + ps;
;   m = mnew;
;   if (__builtin_amdgcn_ballot_w64(alpha != 1.0f)) {
; #pragma unroll
;     for (int dt = 0; dt < 4; ++dt) o[dt] *= alpha;
;   }
.Lnw_slow:
	s_waitcnt vmcnt(15)
	v_mfma_f32_16x16x32_bf16 v[88:91], v[88:91], v[4:7], 0
	s_add_i32 s22, s11, 1
	v_cmp_lt_i32_e32 vcc, s11, v93
	v_mov_b32_e32 v2, s11
	v_mov_b32_e32 v3, s22
	s_waitcnt vmcnt(14)
	v_mfma_f32_16x16x32_bf16 v[84:87], v[84:87], v[8:11], v[88:91]
	v_cndmask_b32_e32 v2, v2, v3, vcc
	s_waitcnt vmcnt(13)
	v_mfma_f32_16x16x32_bf16 v[80:83], v[80:83], v[4:7], 0
	s_waitcnt vmcnt(12)
	v_mfma_f32_16x16x32_bf16 v[76:79], v[76:79], v[8:11], v[80:83]
	s_waitcnt vmcnt(11)
	v_mfma_f32_16x16x32_bf16 v[72:75], v[72:75], v[4:7], 0
	s_waitcnt vmcnt(10)
	v_mfma_f32_16x16x32_bf16 v[68:71], v[68:71], v[8:11], v[72:75]
	s_waitcnt vmcnt(9)
	v_mfma_f32_16x16x32_bf16 v[52:55], v[52:55], v[4:7], 0
	s_waitcnt vmcnt(8)
	v_mfma_f32_16x16x32_bf16 v[44:47], v[44:47], v[8:11], v[52:55]
	v_mov_b32_e32 v92, v98
	v_lshl_add_u32 v2, v2, 6, v0
	v_add_u32_e32 v3, v94, v95
	s_movk_i32 s98, 0x200
	v_sub_u32_e32 v88, v155, v3
	v_mov_b32_e32 v72, v88
	v_add_u32_e32 v73, -1, v88
	v_cmp_gt_u32_e32 vcc, s98, v72
	v_cmp_gt_u32_e64 s[0:1], s98, v73
	v_mul_f32_e32 v74, 0x3e38aa3b, v84
	v_mul_f32_e32 v75, 0x3e38aa3b, v85
	v_cndmask_b32_e32 v99, v203, v74, vcc
	v_cndmask_b32_e64 v100, v203, v75, s[0:1]
	v_add_u32_e32 v72, -2, v88
	v_add_u32_e32 v73, -3, v88
	v_cmp_gt_u32_e32 vcc, s98, v72
	v_cmp_gt_u32_e64 s[0:1], s98, v73
	v_mul_f32_e32 v74, 0x3e38aa3b, v86
	v_mul_f32_e32 v75, 0x3e38aa3b, v87
	v_cndmask_b32_e32 v101, v203, v74, vcc
	v_cndmask_b32_e64 v102, v203, v75, s[0:1]
	v_add_u32_e32 v72, -16, v88
	v_add_u32_e32 v73, -17, v88
	v_cmp_gt_u32_e32 vcc, s98, v72
	v_cmp_gt_u32_e64 s[0:1], s98, v73
	v_mul_f32_e32 v74, 0x3e38aa3b, v76
	v_mul_f32_e32 v75, 0x3e38aa3b, v77
	v_cndmask_b32_e32 v103, v203, v74, vcc
	v_cndmask_b32_e64 v104, v203, v75, s[0:1]
	v_add_u32_e32 v72, -18, v88
	v_add_u32_e32 v73, -19, v88
	v_cmp_gt_u32_e32 vcc, s98, v72
	v_cmp_gt_u32_e64 s[0:1], s98, v73
	v_mul_f32_e32 v74, 0x3e38aa3b, v78
	v_mul_f32_e32 v75, 0x3e38aa3b, v79
	v_cndmask_b32_e32 v105, v203, v74, vcc
	v_cndmask_b32_e64 v106, v203, v75, s[0:1]
	v_add_u32_e32 v72, -32, v88
	v_add_u32_e32 v73, -33, v88
	v_cmp_gt_u32_e32 vcc, s98, v72
	v_cmp_gt_u32_e64 s[0:1], s98, v73
	v_mul_f32_e32 v74, 0x3e38aa3b, v68
	v_mul_f32_e32 v75, 0x3e38aa3b, v69
	v_cndmask_b32_e32 v107, v203, v74, vcc
	v_cndmask_b32_e64 v108, v203, v75, s[0:1]
	v_add_u32_e32 v72, -34, v88
	v_add_u32_e32 v73, -35, v88
	v_cmp_gt_u32_e32 vcc, s98, v72
	v_cmp_gt_u32_e64 s[0:1], s98, v73
	v_mul_f32_e32 v74, 0x3e38aa3b, v70
	v_mul_f32_e32 v75, 0x3e38aa3b, v71
	v_cndmask_b32_e32 v109, v203, v74, vcc
	v_cndmask_b32_e64 v110, v203, v75, s[0:1]
	v_add_u32_e32 v72, -48, v88
	v_add_u32_e32 v73, -49, v88
	v_cmp_gt_u32_e32 vcc, s98, v72
	v_cmp_gt_u32_e64 s[0:1], s98, v73
	v_mul_f32_e32 v74, 0x3e38aa3b, v44
	v_mul_f32_e32 v75, 0x3e38aa3b, v45
	v_cndmask_b32_e32 v111, v203, v74, vcc
	v_cndmask_b32_e64 v112, v203, v75, s[0:1]
	v_add_u32_e32 v72, -50, v88
	v_add_u32_e32 v73, -51, v88
	v_cmp_gt_u32_e32 vcc, s98, v72
	v_cmp_gt_u32_e64 s[0:1], s98, v73
	v_mul_f32_e32 v74, 0x3e38aa3b, v46
	v_mul_f32_e32 v75, 0x3e38aa3b, v47
	v_cndmask_b32_e32 v113, v203, v74, vcc
	v_cndmask_b32_e64 v114, v203, v75, s[0:1]
	v_ashrrev_i32_e32 v3, 31, v2
	v_lshlrev_b64 v[44:45], 7, v[2:3]
	v_lshl_add_u64 v[44:45], v[142:143], 0, v[44:45]
	global_load_dwordx4 v[88:91], v[44:45], off
	global_load_dwordx4 v[84:87], v[44:45], off offset:1024
	global_load_dwordx4 v[80:83], v[44:45], off offset:2048
	global_load_dwordx4 v[76:79], v[44:45], off offset:3072
	v_add_co_u32_e32 v44, vcc, s33, v44
	s_nop 1
	v_addc_co_u32_e32 v45, vcc, 0, v45, vcc
	global_load_dwordx4 v[72:75], v[44:45], off
	global_load_dwordx4 v[68:71], v[44:45], off offset:1024
	global_load_dwordx4 v[52:55], v[44:45], off offset:2048
	s_nop 0
	global_load_dwordx4 v[44:47], v[44:45], off offset:3072
	v_max3_f32 v98, v99, s3, v100
	v_max3_f32 v98, v98, v101, v102
	v_max3_f32 v98, v98, v103, v104
	v_max3_f32 v98, v98, v105, v106
	v_max3_f32 v98, v98, v107, v108
	v_max3_f32 v98, v98, v109, v110
	v_max3_f32 v98, v98, v111, v112
	v_max3_f32 v98, v98, v113, v114
	v_mov_b32_e32 v115, v98
	s_nop 1
	v_permlane16_swap_b32_e32 v115, v98
	v_max_f32_e32 v98, v98, v115
	v_mov_b32_e32 v115, v98
	s_nop 1
	v_permlane32_swap_b32_e32 v115, v98
	v_max3_f32 v98, v92, v98, v115
	v_sub_f32_e32 v92, v92, v98
	v_exp_f32_e32 v92, v92
	s_nop 0
	v_cmp_neq_f32_e32 vcc, 1.0, v92
	s_cbranch_vccz .LBB0_102
	v_pk_mul_f32 v[26:27], v[26:27], v[92:93] op_sel_hi:[1,0]
	v_pk_mul_f32 v[24:25], v[24:25], v[92:93] op_sel_hi:[1,0]
	v_pk_mul_f32 v[22:23], v[22:23], v[92:93] op_sel_hi:[1,0]
	v_pk_mul_f32 v[20:21], v[20:21], v[92:93] op_sel_hi:[1,0]
	v_pk_mul_f32 v[18:19], v[18:19], v[92:93] op_sel_hi:[1,0]
	v_pk_mul_f32 v[16:17], v[16:17], v[92:93] op_sel_hi:[1,0]
	v_pk_mul_f32 v[14:15], v[14:15], v[92:93] op_sel_hi:[1,0]
	v_pk_mul_f32 v[12:13], v[12:13], v[92:93] op_sel_hi:[1,0]
	s_branch .LBB0_102
